# part-1 weight conversion moved from P7 of the previous layer to the P1 phase exit (200 workgroups idle during the eighth tile round)
# speedup vs baseline: 1.0113x; 1.0016x over previous
.LBB0_228:
	s_lshr_b32 s0, s71, 3
	s_cmp_lt_u32 s0, 56
	s_cbranch_scc1 .Lp1conv_skip
	s_cmp_eq_u32 s45, 0
	s_cbranch_scc1 .Lp1conv_skip
	v_readlane_b32 s20, v253, 48
	v_readlane_b32 s0, v253, 2
	v_readlane_b32 s1, v253, 3
	v_readlane_b32 s2, v254, 1
	v_readlane_b32 s3, v254, 2
	v_readlane_b32 s4, v253, 36
	v_readlane_b32 s5, v253, 37
	v_readlane_b32 s6, v253, 38
	v_readlane_b32 s7, v253, 39
	v_readlane_b32 s8, v253, 40
	v_readlane_b32 s9, v253, 41
	v_readlane_b32 s22, v253, 42
	v_readlane_b32 s23, v253, 43
	s_sub_i32 s20, s20, 0x7000
	v_add_u32_e32 v29, s20, v170
	s_lshl_b32 s21, s45, 20
	s_add_u32 s2, s2, s21
	s_addc_u32 s3, s3, 0
	s_lshl_b32 s21, s45, 21
	s_add_u32 s4, s4, s21
	s_addc_u32 s5, s5, 0
	s_add_u32 s6, s6, s21
	s_addc_u32 s7, s7, 0
	s_add_u32 s8, s8, s21
	s_addc_u32 s9, s9, 0
	s_lshl_b32 s21, s45, 22
	s_add_u32 s22, s22, s21
	s_addc_u32 s23, s23, 0
	s_mov_b64 s[20:21], exec
	v_mov_b32_e32 v40, v29
	v_cmp_gt_u32_e32 vcc, 0x20000, v40
	s_mov_b64 s[10:11], vcc
	v_lshrrev_b32_e32 v41, 6, v40
	v_lshrrev_b32_e32 v42, 12, v40
	v_lshlrev_b32_e32 v41, 6, v42
	v_lshrrev_b32_e32 v44, 6, v40
	v_sub_u32_e32 v41, v44, v41
	v_bfe_u32 v44, v40, 4, 2
	v_lshl_add_u32 v44, v42, 2, v44
	v_and_b32_e32 v42, 15, v40
	v_lshl_add_u32 v42, v41, 4, v42
	v_mov_b32_e32 v41, v44
	v_mul_u32_u24_e32 v43, 0x8000, v41
	v_lshl_add_u32 v43, v42, 2, v43
	v_lshlrev_b32_e32 v24, 11, v42
	v_lshl_add_u32 v24, v41, 4, v24
	v_add_u32_e32 v24, 0x1700000, v24
	s_mov_b64 exec, s[10:11]
	global_load_dword v0, v43, s[22:23]
	v_add_u32_e32 v43, 0x1000, v43
	global_load_dword v1, v43, s[22:23]
	v_add_u32_e32 v43, 0x1000, v43
	global_load_dword v2, v43, s[22:23]
	v_add_u32_e32 v43, 0x1000, v43
	global_load_dword v3, v43, s[22:23]
	v_add_u32_e32 v43, 0x1000, v43
	global_load_dword v4, v43, s[22:23]
	v_add_u32_e32 v43, 0x1000, v43
	global_load_dword v5, v43, s[22:23]
	v_add_u32_e32 v43, 0x1000, v43
	global_load_dword v6, v43, s[22:23]
	v_add_u32_e32 v43, 0x1000, v43
	global_load_dword v7, v43, s[22:23]
	s_mov_b64 exec, s[20:21]
	s_mov_b32 s30, 0x19000
	v_add_u32_e32 v40, s30, v29
	v_cmp_gt_u32_e32 vcc, 0x20000, v40
	s_mov_b64 s[12:13], vcc
	v_lshrrev_b32_e32 v41, 6, v40
	v_lshrrev_b32_e32 v42, 12, v40
	v_lshlrev_b32_e32 v41, 6, v42
	v_lshrrev_b32_e32 v44, 6, v40
	v_sub_u32_e32 v41, v44, v41
	v_bfe_u32 v44, v40, 4, 2
	v_lshl_add_u32 v44, v42, 2, v44
	v_and_b32_e32 v42, 15, v40
	v_lshl_add_u32 v42, v41, 4, v42
	v_mov_b32_e32 v41, v44
	v_mul_u32_u24_e32 v43, 0x8000, v41
	v_lshl_add_u32 v43, v42, 2, v43
	v_lshlrev_b32_e32 v25, 11, v42
	v_lshl_add_u32 v25, v41, 4, v25
	v_add_u32_e32 v25, 0x1700000, v25
	s_mov_b64 exec, s[12:13]
	global_load_dword v8, v43, s[22:23]
	v_add_u32_e32 v43, 0x1000, v43
	global_load_dword v9, v43, s[22:23]
	v_add_u32_e32 v43, 0x1000, v43
	global_load_dword v10, v43, s[22:23]
	v_add_u32_e32 v43, 0x1000, v43
	global_load_dword v11, v43, s[22:23]
	v_add_u32_e32 v43, 0x1000, v43
	global_load_dword v12, v43, s[22:23]
	v_add_u32_e32 v43, 0x1000, v43
	global_load_dword v13, v43, s[22:23]
	v_add_u32_e32 v43, 0x1000, v43
	global_load_dword v14, v43, s[22:23]
	v_add_u32_e32 v43, 0x1000, v43
	global_load_dword v15, v43, s[22:23]
	s_mov_b64 exec, s[20:21]
	v_mov_b32_e32 v40, v29
	v_cmp_gt_u32_e32 vcc, 0x10000, v40
	s_mov_b64 s[14:15], vcc
	v_lshrrev_b32_e32 v41, 6, v40
	v_lshrrev_b32_e32 v42, 12, v40
	v_lshlrev_b32_e32 v41, 6, v42
	v_lshrrev_b32_e32 v44, 6, v40
	v_sub_u32_e32 v41, v44, v41
	v_bfe_u32 v44, v40, 4, 2
	v_lshl_add_u32 v44, v42, 2, v44
	v_and_b32_e32 v42, 15, v40
	v_lshl_add_u32 v42, v41, 4, v42
	v_mov_b32_e32 v41, v44
	v_mul_u32_u24_e32 v43, 0x8000, v41
	v_lshl_add_u32 v43, v42, 2, v43
	v_lshlrev_b32_e32 v26, 10, v42
	v_lshl_add_u32 v26, v41, 4, v26
	v_add_u32_e32 v26, 0x1400000, v26
	s_mov_b64 exec, s[14:15]
	global_load_dword v16, v43, s[4:5]
	v_add_u32_e32 v43, 0x1000, v43
	global_load_dword v17, v43, s[4:5]
	v_add_u32_e32 v43, 0x1000, v43
	global_load_dword v18, v43, s[4:5]
	v_add_u32_e32 v43, 0x1000, v43
	global_load_dword v19, v43, s[4:5]
	v_add_u32_e32 v43, 0x1000, v43
	global_load_dword v20, v43, s[4:5]
	v_add_u32_e32 v43, 0x1000, v43
	global_load_dword v21, v43, s[4:5]
	v_add_u32_e32 v43, 0x1000, v43
	global_load_dword v22, v43, s[4:5]
	v_add_u32_e32 v43, 0x1000, v43
	global_load_dword v23, v43, s[4:5]
	s_mov_b64 exec, s[20:21]
	v_mov_b32_e32 v40, v29
	v_cmp_gt_u32_e32 vcc, 0x10000, v40
	s_mov_b64 s[16:17], vcc
	v_lshrrev_b32_e32 v41, 6, v40
	v_lshrrev_b32_e32 v42, 12, v40
	v_lshlrev_b32_e32 v41, 6, v42
	v_lshrrev_b32_e32 v44, 6, v40
	v_sub_u32_e32 v41, v44, v41
	v_bfe_u32 v44, v40, 4, 2
	v_lshl_add_u32 v44, v42, 2, v44
	v_and_b32_e32 v42, 15, v40
	v_lshl_add_u32 v42, v41, 4, v42
	v_mov_b32_e32 v41, v44
	v_mul_u32_u24_e32 v43, 0x8000, v41
	v_lshl_add_u32 v43, v42, 2, v43
	v_lshlrev_b32_e32 v27, 10, v42
	v_lshl_add_u32 v27, v41, 4, v27
	v_add_u32_e32 v27, 0x1500000, v27
	s_mov_b64 exec, s[16:17]
	global_load_dword v32, v43, s[6:7]
	v_add_u32_e32 v43, 0x1000, v43
	global_load_dword v33, v43, s[6:7]
	v_add_u32_e32 v43, 0x1000, v43
	global_load_dword v34, v43, s[6:7]
	v_add_u32_e32 v43, 0x1000, v43
	global_load_dword v35, v43, s[6:7]
	v_add_u32_e32 v43, 0x1000, v43
	global_load_dword v36, v43, s[6:7]
	v_add_u32_e32 v43, 0x1000, v43
	global_load_dword v37, v43, s[6:7]
	v_add_u32_e32 v43, 0x1000, v43
	global_load_dword v38, v43, s[6:7]
	v_add_u32_e32 v43, 0x1000, v43
	global_load_dword v39, v43, s[6:7]
	s_mov_b64 exec, s[20:21]
	v_mov_b32_e32 v40, v29
	v_cmp_gt_u32_e32 vcc, 0x10000, v40
	s_mov_b64 s[18:19], vcc
	v_lshrrev_b32_e32 v41, 6, v40
	v_lshrrev_b32_e32 v42, 12, v40
	v_lshlrev_b32_e32 v41, 6, v42
	v_lshrrev_b32_e32 v44, 6, v40
	v_sub_u32_e32 v41, v44, v41
	v_bfe_u32 v44, v40, 4, 2
	v_lshl_add_u32 v44, v42, 2, v44
	v_and_b32_e32 v42, 15, v40
	v_lshl_add_u32 v42, v41, 4, v42
	v_mov_b32_e32 v41, v44
	v_mul_u32_u24_e32 v43, 0x8000, v41
	v_lshl_add_u32 v43, v42, 2, v43
	v_lshlrev_b32_e32 v28, 10, v42
	v_lshl_add_u32 v28, v41, 4, v28
	v_add_u32_e32 v28, 0x1600000, v28
	s_mov_b64 exec, s[18:19]
	global_load_dword v48, v43, s[8:9]
	v_add_u32_e32 v43, 0x1000, v43
	global_load_dword v49, v43, s[8:9]
	v_add_u32_e32 v43, 0x1000, v43
	global_load_dword v50, v43, s[8:9]
	v_add_u32_e32 v43, 0x1000, v43
	global_load_dword v51, v43, s[8:9]
	v_add_u32_e32 v43, 0x1000, v43
	global_load_dword v52, v43, s[8:9]
	v_add_u32_e32 v43, 0x1000, v43
	global_load_dword v53, v43, s[8:9]
	v_add_u32_e32 v43, 0x1000, v43
	global_load_dword v54, v43, s[8:9]
	v_add_u32_e32 v43, 0x1000, v43
	global_load_dword v55, v43, s[8:9]
	s_mov_b64 exec, s[20:21]
	s_waitcnt vmcnt(0)
	s_mov_b64 exec, s[10:11]
	v_cvt_pk_bf16_f32 v0, v0, v1
	v_cvt_pk_bf16_f32 v1, v2, v3
	v_cvt_pk_bf16_f32 v2, v4, v5
	v_cvt_pk_bf16_f32 v3, v6, v7
	global_store_dwordx4 v24, v[0:3], s[0:1]
	s_mov_b64 exec, s[20:21]
	s_mov_b64 exec, s[12:13]
	v_cvt_pk_bf16_f32 v8, v8, v9
	v_cvt_pk_bf16_f32 v9, v10, v11
	v_cvt_pk_bf16_f32 v10, v12, v13
	v_cvt_pk_bf16_f32 v11, v14, v15
	global_store_dwordx4 v25, v[8:11], s[0:1]
	s_mov_b64 exec, s[20:21]
	s_mov_b64 exec, s[14:15]
	v_cvt_pk_bf16_f32 v16, v16, v17
	v_cvt_pk_bf16_f32 v17, v18, v19
	v_cvt_pk_bf16_f32 v18, v20, v21
	v_cvt_pk_bf16_f32 v19, v22, v23
	global_store_dwordx4 v26, v[16:19], s[0:1]
	s_mov_b64 exec, s[20:21]
	s_mov_b64 exec, s[16:17]
	v_cvt_pk_bf16_f32 v32, v32, v33
	v_cvt_pk_bf16_f32 v33, v34, v35
	v_cvt_pk_bf16_f32 v34, v36, v37
	v_cvt_pk_bf16_f32 v35, v38, v39
	global_store_dwordx4 v27, v[32:35], s[0:1]
	s_mov_b64 exec, s[20:21]
	s_mov_b64 exec, s[18:19]
	v_cvt_pk_bf16_f32 v48, v48, v49
	v_cvt_pk_bf16_f32 v49, v50, v51
	v_cvt_pk_bf16_f32 v50, v52, v53
	v_cvt_pk_bf16_f32 v51, v54, v55
	global_store_dwordx4 v28, v[48:51], s[0:1]
	s_mov_b64 exec, s[20:21]
	v_mov_b32_e32 v40, v29
	v_cmp_gt_u32_e32 vcc, 0x8000, v40
	s_mov_b64 s[10:11], vcc
	v_lshrrev_b32_e32 v41, 6, v40
	v_lshrrev_b32_e32 v42, 11, v40
	v_lshlrev_b32_e32 v41, 5, v42
	v_lshrrev_b32_e32 v44, 6, v40
	v_sub_u32_e32 v41, v44, v41
	v_bfe_u32 v44, v40, 4, 2
	v_lshl_add_u32 v44, v42, 2, v44
	v_and_b32_e32 v42, 15, v40
	v_lshl_add_u32 v42, v41, 4, v42
	v_mov_b32_e32 v41, v44
	v_mul_u32_u24_e32 v43, 0x4000, v41
	v_lshl_add_u32 v43, v42, 2, v43
	v_lshlrev_b32_e32 v24, 10, v42
	v_lshl_add_u32 v24, v41, 4, v24
	v_add_u32_e32 v24, 0x1300000, v24
	s_mov_b64 exec, s[10:11]
	global_load_dword v0, v43, s[2:3]
	v_add_u32_e32 v43, 0x800, v43
	global_load_dword v1, v43, s[2:3]
	v_add_u32_e32 v43, 0x800, v43
	global_load_dword v2, v43, s[2:3]
	v_add_u32_e32 v43, 0x800, v43
	global_load_dword v3, v43, s[2:3]
	v_add_u32_e32 v43, 0x800, v43
	global_load_dword v4, v43, s[2:3]
	v_add_u32_e32 v43, 0x800, v43
	global_load_dword v5, v43, s[2:3]
	v_add_u32_e32 v43, 0x800, v43
	global_load_dword v6, v43, s[2:3]
	v_add_u32_e32 v43, 0x800, v43
	global_load_dword v7, v43, s[2:3]
	s_mov_b64 exec, s[20:21]
	s_waitcnt vmcnt(0)
	s_mov_b64 exec, s[10:11]
	v_cvt_pk_bf16_f32 v0, v0, v1
	v_cvt_pk_bf16_f32 v1, v2, v3
	v_cvt_pk_bf16_f32 v2, v4, v5
	v_cvt_pk_bf16_f32 v3, v6, v7
	global_store_dwordx4 v24, v[0:3], s[0:1]
	s_mov_b64 exec, s[20:21]
	s_nop 0
	s_nop 0
	s_nop 0
	s_nop 0
	s_nop 0
	s_nop 0
	s_nop 0
	s_nop 0

.LBB0_950:
	s_or_b64 exec, exec, s[6:7]
	v_readlane_b32 s0, v253, 4
	v_readlane_b32 s1, v253, 5
	s_andn2_b64 vcc, exec, s[0:1]
	s_branch .LBB0_982
	v_readlane_b32 s20, v253, 48
	v_readlane_b32 s0, v253, 2
	v_readlane_b32 s1, v253, 3
	v_readlane_b32 s2, v254, 1
	v_readlane_b32 s3, v254, 2
	v_readlane_b32 s4, v253, 36
	v_readlane_b32 s5, v253, 37
	v_readlane_b32 s6, v253, 38
	v_readlane_b32 s7, v253, 39
	v_readlane_b32 s8, v253, 40
	v_readlane_b32 s9, v253, 41
	v_readlane_b32 s22, v253, 42
	v_readlane_b32 s23, v253, 43
	v_add_u32_e32 v29, s20, v83
	v_readlane_b32 s20, v255, 29
	s_nop 1
	s_lshl_b32 s21, s20, 20
	s_add_u32 s2, s2, s21
	s_addc_u32 s3, s3, 0
	s_lshl_b32 s21, s20, 21
	s_add_u32 s4, s4, s21
	s_addc_u32 s5, s5, 0
	s_add_u32 s6, s6, s21
	s_addc_u32 s7, s7, 0
	s_add_u32 s8, s8, s21
	s_addc_u32 s9, s9, 0
	s_lshl_b32 s21, s20, 22
	s_add_u32 s22, s22, s21
	s_addc_u32 s23, s23, 0
	s_mov_b64 s[20:21], exec
	v_mov_b32_e32 v40, v29
	v_cmp_gt_u32_e32 vcc, 0x20000, v40
	s_mov_b64 s[10:11], vcc
	v_lshrrev_b32_e32 v41, 6, v40
	v_lshrrev_b32_e32 v42, 12, v40
	v_lshlrev_b32_e32 v41, 6, v42
	v_lshrrev_b32_e32 v44, 6, v40
	v_sub_u32_e32 v41, v44, v41
	v_bfe_u32 v44, v40, 4, 2
	v_lshl_add_u32 v44, v42, 2, v44
	v_and_b32_e32 v42, 15, v40
	v_lshl_add_u32 v42, v41, 4, v42
	v_mov_b32_e32 v41, v44
	v_mul_u32_u24_e32 v43, 0x8000, v41
	v_lshl_add_u32 v43, v42, 2, v43
	v_lshlrev_b32_e32 v24, 11, v42
	v_lshl_add_u32 v24, v41, 4, v24
	v_add_u32_e32 v24, 0x1700000, v24
	s_mov_b64 exec, s[10:11]
	global_load_dword v0, v43, s[22:23]
	v_add_u32_e32 v43, 0x1000, v43
	global_load_dword v1, v43, s[22:23]
	v_add_u32_e32 v43, 0x1000, v43
	global_load_dword v2, v43, s[22:23]
	v_add_u32_e32 v43, 0x1000, v43
	global_load_dword v3, v43, s[22:23]
	v_add_u32_e32 v43, 0x1000, v43
	global_load_dword v4, v43, s[22:23]
	v_add_u32_e32 v43, 0x1000, v43
	global_load_dword v5, v43, s[22:23]
	v_add_u32_e32 v43, 0x1000, v43
	global_load_dword v6, v43, s[22:23]
	v_add_u32_e32 v43, 0x1000, v43
	global_load_dword v7, v43, s[22:23]
	s_mov_b64 exec, s[20:21]
	v_mov_b32_e32 v40, v29
	v_cmp_gt_u32_e32 vcc, 0x10000, v40
	s_mov_b64 s[12:13], vcc
	v_lshrrev_b32_e32 v41, 6, v40
	v_lshrrev_b32_e32 v42, 12, v40
	v_lshlrev_b32_e32 v41, 6, v42
	v_lshrrev_b32_e32 v44, 6, v40
	v_sub_u32_e32 v41, v44, v41
	v_bfe_u32 v44, v40, 4, 2
	v_lshl_add_u32 v44, v42, 2, v44
	v_and_b32_e32 v42, 15, v40
	v_lshl_add_u32 v42, v41, 4, v42
	v_mov_b32_e32 v41, v44
	v_mul_u32_u24_e32 v43, 0x8000, v41
	v_lshl_add_u32 v43, v42, 2, v43
	v_lshlrev_b32_e32 v25, 10, v42
	v_lshl_add_u32 v25, v41, 4, v25
	v_add_u32_e32 v25, 0x1400000, v25
	s_mov_b64 exec, s[12:13]
	global_load_dword v8, v43, s[4:5]
	v_add_u32_e32 v43, 0x1000, v43
	global_load_dword v9, v43, s[4:5]
	v_add_u32_e32 v43, 0x1000, v43
	global_load_dword v10, v43, s[4:5]
	v_add_u32_e32 v43, 0x1000, v43
	global_load_dword v11, v43, s[4:5]
	v_add_u32_e32 v43, 0x1000, v43
	global_load_dword v12, v43, s[4:5]
	v_add_u32_e32 v43, 0x1000, v43
	global_load_dword v13, v43, s[4:5]
	v_add_u32_e32 v43, 0x1000, v43
	global_load_dword v14, v43, s[4:5]
	v_add_u32_e32 v43, 0x1000, v43
	global_load_dword v15, v43, s[4:5]
	s_mov_b64 exec, s[20:21]
	v_mov_b32_e32 v40, v29
	v_cmp_gt_u32_e32 vcc, 0x10000, v40
	s_mov_b64 s[14:15], vcc
	v_lshrrev_b32_e32 v41, 6, v40
	v_lshrrev_b32_e32 v42, 12, v40
	v_lshlrev_b32_e32 v41, 6, v42
	v_lshrrev_b32_e32 v44, 6, v40
	v_sub_u32_e32 v41, v44, v41
	v_bfe_u32 v44, v40, 4, 2
	v_lshl_add_u32 v44, v42, 2, v44
	v_and_b32_e32 v42, 15, v40
	v_lshl_add_u32 v42, v41, 4, v42
	v_mov_b32_e32 v41, v44
	v_mul_u32_u24_e32 v43, 0x8000, v41
	v_lshl_add_u32 v43, v42, 2, v43
	v_lshlrev_b32_e32 v26, 10, v42
	v_lshl_add_u32 v26, v41, 4, v26
	v_add_u32_e32 v26, 0x1500000, v26
	s_mov_b64 exec, s[14:15]
	global_load_dword v16, v43, s[6:7]
	v_add_u32_e32 v43, 0x1000, v43
	global_load_dword v17, v43, s[6:7]
	v_add_u32_e32 v43, 0x1000, v43
	global_load_dword v18, v43, s[6:7]
	v_add_u32_e32 v43, 0x1000, v43
	global_load_dword v19, v43, s[6:7]
	v_add_u32_e32 v43, 0x1000, v43
	global_load_dword v20, v43, s[6:7]
	v_add_u32_e32 v43, 0x1000, v43
	global_load_dword v21, v43, s[6:7]
	v_add_u32_e32 v43, 0x1000, v43
	global_load_dword v22, v43, s[6:7]
	v_add_u32_e32 v43, 0x1000, v43
	global_load_dword v23, v43, s[6:7]
	s_mov_b64 exec, s[20:21]
	v_mov_b32_e32 v40, v29
	v_cmp_gt_u32_e32 vcc, 0x10000, v40
	s_mov_b64 s[16:17], vcc
	v_lshrrev_b32_e32 v41, 6, v40
	v_lshrrev_b32_e32 v42, 12, v40
	v_lshlrev_b32_e32 v41, 6, v42
	v_lshrrev_b32_e32 v44, 6, v40
	v_sub_u32_e32 v41, v44, v41
	v_bfe_u32 v44, v40, 4, 2
	v_lshl_add_u32 v44, v42, 2, v44
	v_and_b32_e32 v42, 15, v40
	v_lshl_add_u32 v42, v41, 4, v42
	v_mov_b32_e32 v41, v44
	v_mul_u32_u24_e32 v43, 0x8000, v41
	v_lshl_add_u32 v43, v42, 2, v43
	v_lshlrev_b32_e32 v27, 10, v42
	v_lshl_add_u32 v27, v41, 4, v27
	v_add_u32_e32 v27, 0x1600000, v27
	s_mov_b64 exec, s[16:17]
	global_load_dword v32, v43, s[8:9]
	v_add_u32_e32 v43, 0x1000, v43
	global_load_dword v33, v43, s[8:9]
	v_add_u32_e32 v43, 0x1000, v43
	global_load_dword v34, v43, s[8:9]
	v_add_u32_e32 v43, 0x1000, v43
	global_load_dword v35, v43, s[8:9]
	v_add_u32_e32 v43, 0x1000, v43
	global_load_dword v36, v43, s[8:9]
	v_add_u32_e32 v43, 0x1000, v43
	global_load_dword v37, v43, s[8:9]
	v_add_u32_e32 v43, 0x1000, v43
	global_load_dword v38, v43, s[8:9]
	v_add_u32_e32 v43, 0x1000, v43
	global_load_dword v39, v43, s[8:9]
	s_mov_b64 exec, s[20:21]
	v_mov_b32_e32 v40, v29
	v_cmp_gt_u32_e32 vcc, 0x8000, v40
	s_mov_b64 s[18:19], vcc
	v_lshrrev_b32_e32 v41, 6, v40
	v_lshrrev_b32_e32 v42, 11, v40
	v_lshlrev_b32_e32 v41, 5, v42
	v_lshrrev_b32_e32 v44, 6, v40
	v_sub_u32_e32 v41, v44, v41
	v_bfe_u32 v44, v40, 4, 2
	v_lshl_add_u32 v44, v42, 2, v44
	v_and_b32_e32 v42, 15, v40
	v_lshl_add_u32 v42, v41, 4, v42
	v_mov_b32_e32 v41, v44
	v_mul_u32_u24_e32 v43, 0x4000, v41
	v_lshl_add_u32 v43, v42, 2, v43
	v_lshlrev_b32_e32 v28, 10, v42
	v_lshl_add_u32 v28, v41, 4, v28
	v_add_u32_e32 v28, 0x1300000, v28
	s_mov_b64 exec, s[18:19]
	global_load_dword v48, v43, s[2:3]
	v_add_u32_e32 v43, 0x800, v43
	global_load_dword v49, v43, s[2:3]
	v_add_u32_e32 v43, 0x800, v43
	global_load_dword v50, v43, s[2:3]
	v_add_u32_e32 v43, 0x800, v43
	global_load_dword v51, v43, s[2:3]
	v_add_u32_e32 v43, 0x800, v43
	global_load_dword v52, v43, s[2:3]
	v_add_u32_e32 v43, 0x800, v43
	global_load_dword v53, v43, s[2:3]
	v_add_u32_e32 v43, 0x800, v43
	global_load_dword v54, v43, s[2:3]
	v_add_u32_e32 v43, 0x800, v43
	global_load_dword v55, v43, s[2:3]
	s_mov_b64 exec, s[20:21]
	s_waitcnt vmcnt(0)
	s_mov_b64 exec, s[10:11]
	v_cvt_pk_bf16_f32 v0, v0, v1
	v_cvt_pk_bf16_f32 v1, v2, v3
	v_cvt_pk_bf16_f32 v2, v4, v5
	v_cvt_pk_bf16_f32 v3, v6, v7
	global_store_dwordx4 v24, v[0:3], s[0:1]
	s_mov_b64 exec, s[20:21]
	s_mov_b64 exec, s[12:13]
	v_cvt_pk_bf16_f32 v8, v8, v9
	v_cvt_pk_bf16_f32 v9, v10, v11
	v_cvt_pk_bf16_f32 v10, v12, v13
	v_cvt_pk_bf16_f32 v11, v14, v15
	global_store_dwordx4 v25, v[8:11], s[0:1]
	s_mov_b64 exec, s[20:21]
	s_mov_b64 exec, s[14:15]
	v_cvt_pk_bf16_f32 v16, v16, v17
	v_cvt_pk_bf16_f32 v17, v18, v19
	v_cvt_pk_bf16_f32 v18, v20, v21
	v_cvt_pk_bf16_f32 v19, v22, v23
	global_store_dwordx4 v26, v[16:19], s[0:1]
	s_mov_b64 exec, s[20:21]
	s_mov_b64 exec, s[16:17]
	v_cvt_pk_bf16_f32 v32, v32, v33
	v_cvt_pk_bf16_f32 v33, v34, v35
	v_cvt_pk_bf16_f32 v34, v36, v37
	v_cvt_pk_bf16_f32 v35, v38, v39
	global_store_dwordx4 v27, v[32:35], s[0:1]
	s_mov_b64 exec, s[20:21]
	s_mov_b64 exec, s[18:19]
	v_cvt_pk_bf16_f32 v48, v48, v49
	v_cvt_pk_bf16_f32 v49, v50, v51
	v_cvt_pk_bf16_f32 v50, v52, v53
	v_cvt_pk_bf16_f32 v51, v54, v55
	global_store_dwordx4 v28, v[48:51], s[0:1]
	s_mov_b64 exec, s[20:21]
